# baseline (speedup 1.0000x reference)
; __device__ __forceinline__ void grid_bar(unsigned* cnt, unsigned target) {
;     ...
;     asm volatile("s_waitcnt vmcnt(0)" ::: "memory");
;     __hip_atomic_fetch_add(cnt, 1u, __ATOMIC_RELAXED, __HIP_MEMORY_SCOPE_AGENT);
;     while (__hip_atomic_load(cnt, __ATOMIC_RELAXED, __HIP_MEMORY_SCOPE_AGENT) < target) __builtin_amdgcn_s_sleep(4);
;     __builtin_amdgcn_fence(__ATOMIC_ACQUIRE, "agent");
.LBB0_84:
	s_sleep 1
	global_load_dword v1, v0, s[30:31] sc1
	s_waitcnt vmcnt(0)
	v_cmp_gt_u32_e32 vcc, s28, v1
	s_cbranch_vccnz .LBB0_84

; __device__ __forceinline__ void grid_bar(unsigned* cnt, unsigned target) {
;     ...
;     asm volatile("s_waitcnt vmcnt(0)" ::: "memory");
;     __hip_atomic_fetch_add(cnt, 1u, __ATOMIC_RELAXED, __HIP_MEMORY_SCOPE_AGENT);
;     while (__hip_atomic_load(cnt, __ATOMIC_RELAXED, __HIP_MEMORY_SCOPE_AGENT) < target) __builtin_amdgcn_s_sleep(4);
;     __builtin_amdgcn_fence(__ATOMIC_ACQUIRE, "agent");
.LBB0_208:
	s_sleep 1
	global_load_dword v1, v0, s[30:31] sc1
	s_waitcnt vmcnt(0)
	v_cmp_gt_u32_e32 vcc, s3, v1
	s_cbranch_vccnz .LBB0_208

; __device__ __forceinline__ void grid_bar(unsigned* cnt, unsigned target) {
;     ...
;     asm volatile("s_waitcnt vmcnt(0)" ::: "memory");
;     __hip_atomic_fetch_add(cnt, 1u, __ATOMIC_RELAXED, __HIP_MEMORY_SCOPE_AGENT);
;     while (__hip_atomic_load(cnt, __ATOMIC_RELAXED, __HIP_MEMORY_SCOPE_AGENT) < target) __builtin_amdgcn_s_sleep(4);
;     __builtin_amdgcn_fence(__ATOMIC_ACQUIRE, "agent");
.LBB0_578:
	s_sleep 1
	global_load_dword v1, v0, s[30:31] sc1
	s_waitcnt vmcnt(0)
	v_cmp_gt_u32_e32 vcc, s4, v1
	s_cbranch_vccnz .LBB0_578
